# GEMM K-loop heads aligned to 64 B (.p2align 6), nothing else changed
# speedup vs baseline: 1.0098x; 1.0011x over previous
; template <class Epi, bool ALIGN_EPI>
; __device__ __forceinline__ void gemm_phase(LAS unsigned char* lds, const Gemm g, const StaticOrder& S, const Epi& E) {
;     ...
;         const bool has_next = S.next(ui + 1, nxt);
;         const char* nA = has_next ? (const char*)g.A + (size_t)nxt.pm * tstepA : cA; const char* nB = has_next ? (const char*)g.Bt + (size_t)nxt.pn * tstepB : cB;
;         for (int t = 0; t < nt; t += 2) {
;             const bool last = (t == nt - 2);
;             const char* a1 = cA + (size_t)(t + 1) * kstep;
;             const char* a2 = last ? nA : cA + (size_t)(t + 2) * kstep; const char* b2 = last ? nB : cB + (size_t)(t + 2) * kstep;
;             const char* a3 = a2 + kstep; const char* b3 = b2 + kstep;
;     ...
;         for (int a = 0; a < 2; ++a)
; #pragma unroll
;             for (int b = 0; b < 2; ++b)
; #pragma unroll
;                 for (int m = 0; m < 4; ++m)
; #pragma unroll
;                     for (int n = 0; n < 2; ++n) acc[a][b][m][n] = (f32x4){0.f, 0.f, 0.f, 0.f};
.LBB0_1261:
	s_ashr_i32 s57, s56, 31
	s_lshl_b64 s[16:17], s[56:57], 19
	s_add_u32 s16, s8, s16
	s_addc_u32 s17, s9, s17
	s_and_b64 s[18:19], s[40:41], exec
	s_cselect_b32 s24, s17, s21
	s_cselect_b32 s25, s16, s20
	s_ashr_i32 s61, s60, 31
	s_lshl_b64 s[18:19], s[60:61], 19
	s_add_u32 s18, s80, s18
	v_readlane_b32 s28, v251, 51
	s_addc_u32 s19, s28, s19
	s_and_b64 s[28:29], s[40:41], exec
	s_cselect_b32 s28, s19, s23
	s_cselect_b32 s29, s18, s22
	s_add_u32 s46, s22, 0x100
	s_addc_u32 s47, s23, 0
	s_add_u32 s20, s20, 0x40080
	v_mov_b32_e32 v0, 0
	s_addc_u32 s21, s21, 0
	s_mov_b32 s54, -2
	v_mov_b32_e32 v1, v0
	v_mov_b32_e32 v2, v0
	v_mov_b32_e32 v3, v0
	v_mov_b32_e32 v10, v0
	v_mov_b32_e32 v11, v0
	v_mov_b32_e32 v12, v0
	v_mov_b32_e32 v13, v0
	v_mov_b32_e32 v18, v0
	v_mov_b32_e32 v19, v0
	v_mov_b32_e32 v20, v0
	v_mov_b32_e32 v21, v0
	v_mov_b32_e32 v26, v0
	v_mov_b32_e32 v27, v0
	v_mov_b32_e32 v28, v0
	v_mov_b32_e32 v29, v0
	v_mov_b32_e32 v34, v0
	v_mov_b32_e32 v35, v0
	v_mov_b32_e32 v36, v0
	v_mov_b32_e32 v37, v0
	v_mov_b32_e32 v42, v0
	v_mov_b32_e32 v43, v0
	v_mov_b32_e32 v44, v0
	v_mov_b32_e32 v45, v0
	v_mov_b32_e32 v50, v0
	v_mov_b32_e32 v51, v0
	v_mov_b32_e32 v52, v0
	v_mov_b32_e32 v53, v0
	v_mov_b32_e32 v58, v0
	v_mov_b32_e32 v59, v0
	v_mov_b32_e32 v60, v0
	v_mov_b32_e32 v61, v0
	v_mov_b32_e32 v6, v0
	v_mov_b32_e32 v7, v0
	v_mov_b32_e32 v8, v0
	v_mov_b32_e32 v9, v0
	v_mov_b32_e32 v14, v0
	v_mov_b32_e32 v15, v0
	v_mov_b32_e32 v16, v0
	v_mov_b32_e32 v17, v0
	v_mov_b32_e32 v22, v0
	v_mov_b32_e32 v23, v0
	v_mov_b32_e32 v24, v0
	v_mov_b32_e32 v25, v0
	v_mov_b32_e32 v30, v0
	v_mov_b32_e32 v31, v0
	v_mov_b32_e32 v32, v0
	v_mov_b32_e32 v33, v0
	v_mov_b32_e32 v38, v0
	v_mov_b32_e32 v39, v0
	v_mov_b32_e32 v40, v0
	v_mov_b32_e32 v41, v0
	v_mov_b32_e32 v46, v0
	v_mov_b32_e32 v47, v0
	v_mov_b32_e32 v48, v0
	v_mov_b32_e32 v49, v0
	v_mov_b32_e32 v54, v0
	v_mov_b32_e32 v55, v0
	v_mov_b32_e32 v56, v0
	v_mov_b32_e32 v57, v0
	v_mov_b32_e32 v62, v0
	v_mov_b32_e32 v63, v0
	v_mov_b32_e32 v64, v0
	v_mov_b32_e32 v65, v0
	v_mov_b32_e32 v66, v0
	v_mov_b32_e32 v67, v0
	v_mov_b32_e32 v68, v0
	v_mov_b32_e32 v69, v0
	v_mov_b32_e32 v74, v0
	v_mov_b32_e32 v75, v0
	v_mov_b32_e32 v76, v0
	v_mov_b32_e32 v77, v0
	v_mov_b32_e32 v82, v0
	v_mov_b32_e32 v83, v0
	v_mov_b32_e32 v84, v0
	v_mov_b32_e32 v85, v0
	v_mov_b32_e32 v90, v0
	v_mov_b32_e32 v91, v0
	v_mov_b32_e32 v92, v0
	v_mov_b32_e32 v93, v0
	s_waitcnt vmcnt(0)
	v_mov_b32_e32 v98, v0
	v_mov_b32_e32 v99, v0
	v_mov_b32_e32 v100, v0
	v_mov_b32_e32 v101, v0
	v_mov_b32_e32 v106, v0
	v_mov_b32_e32 v107, v0
	v_mov_b32_e32 v108, v0
	v_mov_b32_e32 v109, v0
	v_mov_b32_e32 v114, v0
	v_mov_b32_e32 v115, v0
	v_mov_b32_e32 v116, v0
	v_mov_b32_e32 v117, v0
	v_mov_b32_e32 v122, v0
	v_mov_b32_e32 v123, v0
	v_mov_b32_e32 v124, v0
	v_mov_b32_e32 v125, v0
	v_mov_b32_e32 v70, v0
	v_mov_b32_e32 v71, v0
	v_mov_b32_e32 v72, v0
	v_mov_b32_e32 v73, v0
	v_mov_b32_e32 v78, v0
	v_mov_b32_e32 v79, v0
	v_mov_b32_e32 v80, v0
	v_mov_b32_e32 v81, v0
	v_mov_b32_e32 v86, v0
	v_mov_b32_e32 v87, v0
	v_mov_b32_e32 v88, v0
	v_mov_b32_e32 v89, v0
	v_mov_b32_e32 v94, v0
	v_mov_b32_e32 v95, v0
	v_mov_b32_e32 v96, v0
	v_mov_b32_e32 v97, v0
	v_mov_b32_e32 v102, v0
	v_mov_b32_e32 v103, v0
	v_mov_b32_e32 v104, v0
	v_mov_b32_e32 v105, v0
	v_mov_b32_e32 v110, v0
	v_mov_b32_e32 v111, v0
	v_mov_b32_e32 v112, v0
	v_mov_b32_e32 v113, v0
	v_mov_b32_e32 v118, v0
	v_mov_b32_e32 v119, v0
	v_mov_b32_e32 v120, v0
	v_mov_b32_e32 v121, v0
	v_mov_b32_e32 v126, v0
	v_mov_b32_e32 v127, v0
	v_mov_b32_e32 v128, v0
	v_mov_b32_e32 v129, v0
	.p2align	6

; template <class Epi, bool ALIGN_EPI>
; __device__ __forceinline__ void gemm_phase(LAS unsigned char* lds, const Gemm g, const StaticOrder& S, const Epi& E) {
;     ...
;         for (int a = 0; a < 2; ++a)
; #pragma unroll
;             for (int b = 0; b < 2; ++b)
; #pragma unroll
;                 for (int m = 0; m < 4; ++m)
; #pragma unroll
;                     for (int n = 0; n < 2; ++n) acc[a][b][m][n] = (f32x4){0.f, 0.f, 0.f, 0.f};
.LBB0_1291:
	s_add_u32 s28, s96, 0x100
	s_addc_u32 s29, s97, 0
	s_add_u32 s44, s50, 0x80
	v_mov_b32_e32 v0, 0
	s_addc_u32 s45, s51, 0
	s_mov_b32 s50, 0
	v_mov_b32_e32 v1, v0
	v_mov_b32_e32 v2, v0
	v_mov_b32_e32 v3, v0
	v_mov_b32_e32 v6, v0
	v_mov_b32_e32 v7, v0
	v_mov_b32_e32 v8, v0
	v_mov_b32_e32 v9, v0
	v_mov_b32_e32 v14, v0
	v_mov_b32_e32 v15, v0
	v_mov_b32_e32 v16, v0
	v_mov_b32_e32 v17, v0
	v_mov_b32_e32 v22, v0
	v_mov_b32_e32 v23, v0
	v_mov_b32_e32 v24, v0
	v_mov_b32_e32 v25, v0
	v_mov_b32_e32 v34, v0
	v_mov_b32_e32 v35, v0
	v_mov_b32_e32 v36, v0
	v_mov_b32_e32 v37, v0
	v_mov_b32_e32 v38, v0
	v_mov_b32_e32 v39, v0
	v_mov_b32_e32 v40, v0
	v_mov_b32_e32 v41, v0
	v_mov_b32_e32 v50, v0
	v_mov_b32_e32 v51, v0
	v_mov_b32_e32 v52, v0
	v_mov_b32_e32 v53, v0
	v_mov_b32_e32 v54, v0
	v_mov_b32_e32 v55, v0
	v_mov_b32_e32 v56, v0
	v_mov_b32_e32 v57, v0
	v_mov_b32_e32 v10, v0
	v_mov_b32_e32 v11, v0
	v_mov_b32_e32 v12, v0
	v_mov_b32_e32 v13, v0
	v_mov_b32_e32 v18, v0
	v_mov_b32_e32 v19, v0
	v_mov_b32_e32 v20, v0
	v_mov_b32_e32 v21, v0
	v_mov_b32_e32 v26, v0
	v_mov_b32_e32 v27, v0
	v_mov_b32_e32 v28, v0
	v_mov_b32_e32 v29, v0
	v_mov_b32_e32 v30, v0
	v_mov_b32_e32 v31, v0
	v_mov_b32_e32 v32, v0
	v_mov_b32_e32 v33, v0
	v_mov_b32_e32 v42, v0
	v_mov_b32_e32 v43, v0
	v_mov_b32_e32 v44, v0
	v_mov_b32_e32 v45, v0
	v_mov_b32_e32 v46, v0
	v_mov_b32_e32 v47, v0
	v_mov_b32_e32 v48, v0
	v_mov_b32_e32 v49, v0
	v_mov_b32_e32 v58, v0
	v_mov_b32_e32 v59, v0
	v_mov_b32_e32 v60, v0
	v_mov_b32_e32 v61, v0
	v_mov_b32_e32 v62, v0
	v_mov_b32_e32 v63, v0
	v_mov_b32_e32 v64, v0
	v_mov_b32_e32 v65, v0
	v_mov_b32_e32 v66, v0
	v_mov_b32_e32 v67, v0
	v_mov_b32_e32 v68, v0
	v_mov_b32_e32 v69, v0
	v_mov_b32_e32 v70, v0
	v_mov_b32_e32 v71, v0
	v_mov_b32_e32 v72, v0
	v_mov_b32_e32 v73, v0
	v_mov_b32_e32 v82, v0
	v_mov_b32_e32 v83, v0
	v_mov_b32_e32 v84, v0
	v_mov_b32_e32 v85, v0
	v_mov_b32_e32 v86, v0
	v_mov_b32_e32 v87, v0
	v_mov_b32_e32 v88, v0
	v_mov_b32_e32 v89, v0
	s_waitcnt vmcnt(0)
	v_mov_b32_e32 v98, v0
	v_mov_b32_e32 v99, v0
	v_mov_b32_e32 v100, v0
	v_mov_b32_e32 v101, v0
	v_mov_b32_e32 v102, v0
	v_mov_b32_e32 v103, v0
	v_mov_b32_e32 v104, v0
	v_mov_b32_e32 v105, v0
	v_mov_b32_e32 v114, v0
	v_mov_b32_e32 v115, v0
	v_mov_b32_e32 v116, v0
	v_mov_b32_e32 v117, v0
	v_mov_b32_e32 v118, v0
	v_mov_b32_e32 v119, v0
	v_mov_b32_e32 v120, v0
	v_mov_b32_e32 v121, v0
	v_mov_b32_e32 v74, v0
	v_mov_b32_e32 v75, v0
	v_mov_b32_e32 v76, v0
	v_mov_b32_e32 v77, v0
	v_mov_b32_e32 v78, v0
	v_mov_b32_e32 v79, v0
	v_mov_b32_e32 v80, v0
	v_mov_b32_e32 v81, v0
	v_mov_b32_e32 v90, v0
	v_mov_b32_e32 v91, v0
	v_mov_b32_e32 v92, v0
	v_mov_b32_e32 v93, v0
	v_mov_b32_e32 v94, v0
	v_mov_b32_e32 v95, v0
	v_mov_b32_e32 v96, v0
	v_mov_b32_e32 v97, v0
	v_mov_b32_e32 v106, v0
	v_mov_b32_e32 v107, v0
	v_mov_b32_e32 v108, v0
	v_mov_b32_e32 v109, v0
	v_mov_b32_e32 v110, v0
	v_mov_b32_e32 v111, v0
	v_mov_b32_e32 v112, v0
	v_mov_b32_e32 v113, v0
	v_mov_b32_e32 v122, v0
	v_mov_b32_e32 v123, v0
	v_mov_b32_e32 v124, v0
	v_mov_b32_e32 v125, v0
	v_mov_b32_e32 v126, v0
	v_mov_b32_e32 v127, v0
	v_mov_b32_e32 v128, v0
	v_mov_b32_e32 v129, v0
	.p2align	6

; template <class Epi, bool ALIGN_EPI>
; __device__ __forceinline__ void gemm_phase(LAS unsigned char* lds, const Gemm g, const StaticOrder& S, const Epi& E) {
;     ...
;         const bool has_next = S.next(ui + 1, nxt);
;         const char* nA = has_next ? (const char*)g.A + (size_t)nxt.pm * tstepA : cA; const char* nB = has_next ? (const char*)g.Bt + (size_t)nxt.pn * tstepB : cB;
;         for (int t = 0; t < nt; t += 2) {
;             const bool last = (t == nt - 2);
;             const char* a1 = cA + (size_t)(t + 1) * kstep;
;             const char* a2 = last ? nA : cA + (size_t)(t + 2) * kstep; const char* b2 = last ? nB : cB + (size_t)(t + 2) * kstep;
;             const char* a3 = a2 + kstep; const char* b3 = b2 + kstep;
;     ...
;         for (int a = 0; a < 2; ++a)
; #pragma unroll
;             for (int b = 0; b < 2; ++b)
; #pragma unroll
;                 for (int m = 0; m < 4; ++m)
; #pragma unroll
;                     for (int n = 0; n < 2; ++n) acc[a][b][m][n] = (f32x4){0.f, 0.f, 0.f, 0.f};
.LBB0_1363:
	s_ashr_i32 s45, s44, 31
	s_lshl_b64 s[48:49], s[44:45], 18
	s_add_u32 s48, s7, s48
	s_addc_u32 s49, s4, s49
	s_and_b64 s[56:57], s[40:41], exec
	s_cselect_b32 s43, s49, s97
	s_cselect_b32 s45, s48, s96
	s_ashr_i32 s23, s22, 31
	s_lshl_b64 s[56:57], s[22:23], 18
	s_add_u32 s56, s46, s56
	s_addc_u32 s57, s47, s57
	s_and_b64 s[68:69], s[40:41], exec
	s_cselect_b32 s23, s57, s51
	s_cselect_b32 s61, s56, s50
	s_add_u32 s64, s50, 0x100
	s_addc_u32 s70, s51, 0
	s_add_u32 s96, s96, 0x20080
	v_mov_b32_e32 v0, 0
	s_addc_u32 s97, s97, 0
	s_mov_b32 s71, -2
	v_mov_b32_e32 v1, v0
	v_mov_b32_e32 v2, v0
	v_mov_b32_e32 v3, v0
	v_mov_b32_e32 v6, v0
	v_mov_b32_e32 v7, v0
	v_mov_b32_e32 v8, v0
	v_mov_b32_e32 v9, v0
	v_mov_b32_e32 v14, v0
	v_mov_b32_e32 v15, v0
	v_mov_b32_e32 v16, v0
	v_mov_b32_e32 v17, v0
	v_mov_b32_e32 v22, v0
	v_mov_b32_e32 v23, v0
	v_mov_b32_e32 v24, v0
	v_mov_b32_e32 v25, v0
	v_mov_b32_e32 v34, v0
	v_mov_b32_e32 v35, v0
	v_mov_b32_e32 v36, v0
	v_mov_b32_e32 v37, v0
	v_mov_b32_e32 v38, v0
	v_mov_b32_e32 v39, v0
	v_mov_b32_e32 v40, v0
	v_mov_b32_e32 v41, v0
	v_mov_b32_e32 v50, v0
	v_mov_b32_e32 v51, v0
	v_mov_b32_e32 v52, v0
	v_mov_b32_e32 v53, v0
	v_mov_b32_e32 v54, v0
	v_mov_b32_e32 v55, v0
	v_mov_b32_e32 v56, v0
	v_mov_b32_e32 v57, v0
	v_mov_b32_e32 v10, v0
	v_mov_b32_e32 v11, v0
	v_mov_b32_e32 v12, v0
	v_mov_b32_e32 v13, v0
	v_mov_b32_e32 v18, v0
	v_mov_b32_e32 v19, v0
	v_mov_b32_e32 v20, v0
	v_mov_b32_e32 v21, v0
	v_mov_b32_e32 v26, v0
	v_mov_b32_e32 v27, v0
	v_mov_b32_e32 v28, v0
	v_mov_b32_e32 v29, v0
	v_mov_b32_e32 v30, v0
	v_mov_b32_e32 v31, v0
	v_mov_b32_e32 v32, v0
	v_mov_b32_e32 v33, v0
	v_mov_b32_e32 v42, v0
	v_mov_b32_e32 v43, v0
	v_mov_b32_e32 v44, v0
	v_mov_b32_e32 v45, v0
	v_mov_b32_e32 v46, v0
	v_mov_b32_e32 v47, v0
	v_mov_b32_e32 v48, v0
	v_mov_b32_e32 v49, v0
	v_mov_b32_e32 v58, v0
	v_mov_b32_e32 v59, v0
	v_mov_b32_e32 v60, v0
	v_mov_b32_e32 v61, v0
	v_mov_b32_e32 v62, v0
	v_mov_b32_e32 v63, v0
	v_mov_b32_e32 v64, v0
	v_mov_b32_e32 v65, v0
	v_mov_b32_e32 v66, v0
	v_mov_b32_e32 v67, v0
	v_mov_b32_e32 v68, v0
	v_mov_b32_e32 v69, v0
	v_mov_b32_e32 v70, v0
	v_mov_b32_e32 v71, v0
	v_mov_b32_e32 v72, v0
	v_mov_b32_e32 v73, v0
	v_mov_b32_e32 v82, v0
	v_mov_b32_e32 v83, v0
	v_mov_b32_e32 v84, v0
	v_mov_b32_e32 v85, v0
	v_mov_b32_e32 v86, v0
	v_mov_b32_e32 v87, v0
	v_mov_b32_e32 v88, v0
	v_mov_b32_e32 v89, v0
	s_waitcnt vmcnt(0)
	v_mov_b32_e32 v98, v0
	v_mov_b32_e32 v99, v0
	v_mov_b32_e32 v100, v0
	v_mov_b32_e32 v101, v0
	v_mov_b32_e32 v102, v0
	v_mov_b32_e32 v103, v0
	v_mov_b32_e32 v104, v0
	v_mov_b32_e32 v105, v0
	v_mov_b32_e32 v114, v0
	v_mov_b32_e32 v115, v0
	v_mov_b32_e32 v116, v0
	v_mov_b32_e32 v117, v0
	v_mov_b32_e32 v118, v0
	v_mov_b32_e32 v119, v0
	v_mov_b32_e32 v120, v0
	v_mov_b32_e32 v121, v0
	v_mov_b32_e32 v74, v0
	v_mov_b32_e32 v75, v0
	v_mov_b32_e32 v76, v0
	v_mov_b32_e32 v77, v0
	v_mov_b32_e32 v78, v0
	v_mov_b32_e32 v79, v0
	v_mov_b32_e32 v80, v0
	v_mov_b32_e32 v81, v0
	v_mov_b32_e32 v90, v0
	v_mov_b32_e32 v91, v0
	v_mov_b32_e32 v92, v0
	v_mov_b32_e32 v93, v0
	v_mov_b32_e32 v94, v0
	v_mov_b32_e32 v95, v0
	v_mov_b32_e32 v96, v0
	v_mov_b32_e32 v97, v0
	v_mov_b32_e32 v106, v0
	v_mov_b32_e32 v107, v0
	v_mov_b32_e32 v108, v0
	v_mov_b32_e32 v109, v0
	v_mov_b32_e32 v110, v0
	v_mov_b32_e32 v111, v0
	v_mov_b32_e32 v112, v0
	v_mov_b32_e32 v113, v0
	v_mov_b32_e32 v122, v0
	v_mov_b32_e32 v123, v0
	v_mov_b32_e32 v124, v0
	v_mov_b32_e32 v125, v0
	v_mov_b32_e32 v126, v0
	v_mov_b32_e32 v127, v0
	v_mov_b32_e32 v128, v0
	v_mov_b32_e32 v129, v0
	.p2align	6

; template <class Epi, bool ALIGN_EPI>
; __device__ __forceinline__ void gemm_phase(LAS unsigned char* lds, const Gemm g, const StaticOrder& S, const Epi& E) {
;     ...
;         for (int a = 0; a < 2; ++a)
; #pragma unroll
;             for (int b = 0; b < 2; ++b)
; #pragma unroll
;                 for (int m = 0; m < 4; ++m)
; #pragma unroll
;                     for (int n = 0; n < 2; ++n) acc[a][b][m][n] = (f32x4){0.f, 0.f, 0.f, 0.f};
.LBB0_1426:
	s_add_u32 s56, s56, 0x100
	v_mov_b32_e32 v0, 0
	s_addc_u32 s57, s57, 0
	s_mov_b32 s50, 0
	v_mov_b32_e32 v1, v0
	v_mov_b32_e32 v2, v0
	v_mov_b32_e32 v3, v0
	v_mov_b32_e32 v6, v0
	v_mov_b32_e32 v7, v0
	v_mov_b32_e32 v8, v0
	v_mov_b32_e32 v9, v0
	v_mov_b32_e32 v18, v0
	v_mov_b32_e32 v19, v0
	v_mov_b32_e32 v20, v0
	v_mov_b32_e32 v21, v0
	v_mov_b32_e32 v22, v0
	v_mov_b32_e32 v23, v0
	v_mov_b32_e32 v24, v0
	v_mov_b32_e32 v25, v0
	v_mov_b32_e32 v34, v0
	v_mov_b32_e32 v35, v0
	v_mov_b32_e32 v36, v0
	v_mov_b32_e32 v37, v0
	v_mov_b32_e32 v38, v0
	v_mov_b32_e32 v39, v0
	v_mov_b32_e32 v40, v0
	v_mov_b32_e32 v41, v0
	v_mov_b32_e32 v50, v0
	v_mov_b32_e32 v51, v0
	v_mov_b32_e32 v52, v0
	v_mov_b32_e32 v53, v0
	v_mov_b32_e32 v54, v0
	v_mov_b32_e32 v55, v0
	v_mov_b32_e32 v56, v0
	v_mov_b32_e32 v57, v0
	v_mov_b32_e32 v10, v0
	v_mov_b32_e32 v11, v0
	v_mov_b32_e32 v12, v0
	v_mov_b32_e32 v13, v0
	v_mov_b32_e32 v14, v0
	v_mov_b32_e32 v15, v0
	v_mov_b32_e32 v16, v0
	v_mov_b32_e32 v17, v0
	v_mov_b32_e32 v26, v0
	v_mov_b32_e32 v27, v0
	v_mov_b32_e32 v28, v0
	v_mov_b32_e32 v29, v0
	v_mov_b32_e32 v30, v0
	v_mov_b32_e32 v31, v0
	v_mov_b32_e32 v32, v0
	v_mov_b32_e32 v33, v0
	v_mov_b32_e32 v42, v0
	v_mov_b32_e32 v43, v0
	v_mov_b32_e32 v44, v0
	v_mov_b32_e32 v45, v0
	v_mov_b32_e32 v46, v0
	v_mov_b32_e32 v47, v0
	v_mov_b32_e32 v48, v0
	v_mov_b32_e32 v49, v0
	v_mov_b32_e32 v58, v0
	v_mov_b32_e32 v59, v0
	v_mov_b32_e32 v60, v0
	v_mov_b32_e32 v61, v0
	v_mov_b32_e32 v62, v0
	v_mov_b32_e32 v63, v0
	v_mov_b32_e32 v64, v0
	v_mov_b32_e32 v65, v0
	v_mov_b32_e32 v66, v0
	v_mov_b32_e32 v67, v0
	v_mov_b32_e32 v68, v0
	v_mov_b32_e32 v69, v0
	v_mov_b32_e32 v70, v0
	v_mov_b32_e32 v71, v0
	v_mov_b32_e32 v72, v0
	v_mov_b32_e32 v73, v0
	v_mov_b32_e32 v82, v0
	v_mov_b32_e32 v83, v0
	v_mov_b32_e32 v84, v0
	v_mov_b32_e32 v85, v0
	v_mov_b32_e32 v86, v0
	v_mov_b32_e32 v87, v0
	v_mov_b32_e32 v88, v0
	v_mov_b32_e32 v89, v0
	v_mov_b32_e32 v98, v0
	v_mov_b32_e32 v99, v0
	v_mov_b32_e32 v100, v0
	v_mov_b32_e32 v101, v0
	v_mov_b32_e32 v102, v0
	v_mov_b32_e32 v103, v0
	v_mov_b32_e32 v104, v0
	v_mov_b32_e32 v105, v0
	v_mov_b32_e32 v114, v0
	v_mov_b32_e32 v115, v0
	v_mov_b32_e32 v116, v0
	v_mov_b32_e32 v117, v0
	v_mov_b32_e32 v118, v0
	v_mov_b32_e32 v119, v0
	v_mov_b32_e32 v120, v0
	v_mov_b32_e32 v121, v0
	v_mov_b32_e32 v74, v0
	v_mov_b32_e32 v75, v0
	v_mov_b32_e32 v76, v0
	v_mov_b32_e32 v77, v0
	v_mov_b32_e32 v78, v0
	v_mov_b32_e32 v79, v0
	v_mov_b32_e32 v80, v0
	v_mov_b32_e32 v81, v0
	v_mov_b32_e32 v90, v0
	v_mov_b32_e32 v91, v0
	v_mov_b32_e32 v92, v0
	v_mov_b32_e32 v93, v0
	v_mov_b32_e32 v94, v0
	v_mov_b32_e32 v95, v0
	v_mov_b32_e32 v96, v0
	v_mov_b32_e32 v97, v0
	v_mov_b32_e32 v106, v0
	v_mov_b32_e32 v107, v0
	v_mov_b32_e32 v108, v0
	v_mov_b32_e32 v109, v0
	v_mov_b32_e32 v110, v0
	v_mov_b32_e32 v111, v0
	v_mov_b32_e32 v112, v0
	v_mov_b32_e32 v113, v0
	v_mov_b32_e32 v122, v0
	v_mov_b32_e32 v123, v0
	v_mov_b32_e32 v124, v0
	v_mov_b32_e32 v125, v0
	v_mov_b32_e32 v126, v0
	v_mov_b32_e32 v127, v0
	v_mov_b32_e32 v128, v0
	v_mov_b32_e32 v129, v0
	.p2align	6

; template <class Epi, bool ALIGN_EPI>
; __device__ __forceinline__ void gemm_phase(LAS unsigned char* lds, const Gemm g, const StaticOrder& S, const Epi& E) {
;     ...
;         const bool has_next = S.next(ui + 1, nxt);
;         const char* nA = has_next ? (const char*)g.A + (size_t)nxt.pm * tstepA : cA; const char* nB = has_next ? (const char*)g.Bt + (size_t)nxt.pn * tstepB : cB;
;         for (int t = 0; t < nt; t += 2) {
;             const bool last = (t == nt - 2);
;             const char* a1 = cA + (size_t)(t + 1) * kstep;
;             const char* a2 = last ? nA : cA + (size_t)(t + 2) * kstep; const char* b2 = last ? nB : cB + (size_t)(t + 2) * kstep;
;             const char* a3 = a2 + kstep; const char* b3 = b2 + kstep;
;     ...
;         for (int a = 0; a < 2; ++a)
; #pragma unroll
;             for (int b = 0; b < 2; ++b)
; #pragma unroll
;                 for (int m = 0; m < 4; ++m)
; #pragma unroll
;                     for (int n = 0; n < 2; ++n) acc[a][b][m][n] = (f32x4){0.f, 0.f, 0.f, 0.f};
.LBB0_1482:
	s_ashr_i32 s45, s44, 31
	s_lshl_b64 s[24:25], s[44:45], 19
	s_add_u32 s48, s8, s24
	s_addc_u32 s49, s9, s25
	s_and_b64 s[24:25], s[40:41], exec
	s_cselect_b32 s7, s49, s51
	s_cselect_b32 s21, s48, s50
	s_ashr_i32 s19, s18, 31
	s_lshl_b64 s[24:25], s[18:19], 19
	s_add_u32 s56, s5, s24
	s_addc_u32 s57, s53, s25
	s_and_b64 s[24:25], s[40:41], exec
	s_cselect_b32 s19, s57, s43
	s_cselect_b32 s23, s56, s42
	s_add_u32 s24, s42, 0x100
	s_addc_u32 s25, s43, 0
	s_add_u32 s42, s50, 0x40080
	v_mov_b32_e32 v0, 0
	s_addc_u32 s43, s51, 0
	s_mov_b32 s28, -2
	v_mov_b32_e32 v1, v0
	v_mov_b32_e32 v2, v0
	v_mov_b32_e32 v3, v0
	v_mov_b32_e32 v6, v0
	v_mov_b32_e32 v7, v0
	v_mov_b32_e32 v8, v0
	v_mov_b32_e32 v9, v0
	v_mov_b32_e32 v18, v0
	v_mov_b32_e32 v19, v0
	v_mov_b32_e32 v20, v0
	v_mov_b32_e32 v21, v0
	v_mov_b32_e32 v22, v0
	v_mov_b32_e32 v23, v0
	v_mov_b32_e32 v24, v0
	v_mov_b32_e32 v25, v0
	v_mov_b32_e32 v34, v0
	v_mov_b32_e32 v35, v0
	v_mov_b32_e32 v36, v0
	v_mov_b32_e32 v37, v0
	v_mov_b32_e32 v38, v0
	v_mov_b32_e32 v39, v0
	v_mov_b32_e32 v40, v0
	v_mov_b32_e32 v41, v0
	v_mov_b32_e32 v50, v0
	v_mov_b32_e32 v51, v0
	v_mov_b32_e32 v52, v0
	v_mov_b32_e32 v53, v0
	v_mov_b32_e32 v54, v0
	v_mov_b32_e32 v55, v0
	v_mov_b32_e32 v56, v0
	v_mov_b32_e32 v57, v0
	v_mov_b32_e32 v10, v0
	v_mov_b32_e32 v11, v0
	v_mov_b32_e32 v12, v0
	v_mov_b32_e32 v13, v0
	v_mov_b32_e32 v14, v0
	v_mov_b32_e32 v15, v0
	v_mov_b32_e32 v16, v0
	v_mov_b32_e32 v17, v0
	v_mov_b32_e32 v26, v0
	v_mov_b32_e32 v27, v0
	v_mov_b32_e32 v28, v0
	v_mov_b32_e32 v29, v0
	v_mov_b32_e32 v30, v0
	v_mov_b32_e32 v31, v0
	v_mov_b32_e32 v32, v0
	v_mov_b32_e32 v33, v0
	v_mov_b32_e32 v42, v0
	v_mov_b32_e32 v43, v0
	v_mov_b32_e32 v44, v0
	v_mov_b32_e32 v45, v0
	v_mov_b32_e32 v46, v0
	v_mov_b32_e32 v47, v0
	v_mov_b32_e32 v48, v0
	v_mov_b32_e32 v49, v0
	v_mov_b32_e32 v58, v0
	v_mov_b32_e32 v59, v0
	v_mov_b32_e32 v60, v0
	v_mov_b32_e32 v61, v0
	v_mov_b32_e32 v62, v0
	v_mov_b32_e32 v63, v0
	v_mov_b32_e32 v64, v0
	v_mov_b32_e32 v65, v0
	v_mov_b32_e32 v66, v0
	v_mov_b32_e32 v67, v0
	v_mov_b32_e32 v68, v0
	v_mov_b32_e32 v69, v0
	v_mov_b32_e32 v70, v0
	v_mov_b32_e32 v71, v0
	v_mov_b32_e32 v72, v0
	v_mov_b32_e32 v73, v0
	v_mov_b32_e32 v82, v0
	v_mov_b32_e32 v83, v0
	v_mov_b32_e32 v84, v0
	v_mov_b32_e32 v85, v0
	v_mov_b32_e32 v86, v0
	v_mov_b32_e32 v87, v0
	v_mov_b32_e32 v88, v0
	v_mov_b32_e32 v89, v0
	v_mov_b32_e32 v98, v0
	v_mov_b32_e32 v99, v0
	v_mov_b32_e32 v100, v0
	v_mov_b32_e32 v101, v0
	v_mov_b32_e32 v102, v0
	v_mov_b32_e32 v103, v0
	v_mov_b32_e32 v104, v0
	v_mov_b32_e32 v105, v0
	v_mov_b32_e32 v114, v0
	v_mov_b32_e32 v115, v0
	v_mov_b32_e32 v116, v0
	v_mov_b32_e32 v117, v0
	v_mov_b32_e32 v118, v0
	v_mov_b32_e32 v119, v0
	v_mov_b32_e32 v120, v0
	v_mov_b32_e32 v121, v0
	v_mov_b32_e32 v74, v0
	v_mov_b32_e32 v75, v0
	v_mov_b32_e32 v76, v0
	v_mov_b32_e32 v77, v0
	v_mov_b32_e32 v78, v0
	v_mov_b32_e32 v79, v0
	v_mov_b32_e32 v80, v0
	v_mov_b32_e32 v81, v0
	v_mov_b32_e32 v90, v0
	v_mov_b32_e32 v91, v0
	v_mov_b32_e32 v92, v0
	v_mov_b32_e32 v93, v0
	v_mov_b32_e32 v94, v0
	v_mov_b32_e32 v95, v0
	v_mov_b32_e32 v96, v0
	v_mov_b32_e32 v97, v0
	v_mov_b32_e32 v106, v0
	v_mov_b32_e32 v107, v0
	v_mov_b32_e32 v108, v0
	v_mov_b32_e32 v109, v0
	v_mov_b32_e32 v110, v0
	v_mov_b32_e32 v111, v0
	v_mov_b32_e32 v112, v0
	v_mov_b32_e32 v113, v0
	v_mov_b32_e32 v122, v0
	v_mov_b32_e32 v123, v0
	v_mov_b32_e32 v124, v0
	v_mov_b32_e32 v125, v0
	v_mov_b32_e32 v126, v0
	v_mov_b32_e32 v127, v0
	v_mov_b32_e32 v128, v0
	v_mov_b32_e32 v129, v0
	.p2align	6
